# phase-2 next-item q/k/LR loads back at the baseline site with counted vmcnt(2) waits (no early prefetch block, no handover movs)
# speedup vs baseline: 1.0022x; 1.0022x over previous
; #define LAS __attribute__((address_space(3)))
; __device__ __forceinline__ void phase_gla_pre(const Params& P, LAS unsigned char* lds, bool dry) {
;     ...
;     for (; item < 2048; item += gridDim.x) {
;         const int bh = item >> 6, c = item & 63, b = bh >> 2, h = bh & 3, row0 = b * SEQ + c * 64;
;         if (tid < 256) *(LAS f32x4*)(Llr + 4 * tid) = rl;
;         bf16x8 bhi = (bf16x8){0, 0, 0, 0, 0, 0, 0, 0}, blo = bhi;
;         if (g < 2) { f32x4 w0, w1;
; #pragma unroll
;             for (int j = 0; j < 4; ++j) { w0[j] = P.w_gate_up[(8 * g + j) * 512 + h * 128 + 16 * w + fr]; w1[j] = P.w_gate_up[(8 * g + 4 + j) * 512 + h * 128 + 16 * w + fr]; }
;             split8(w0, w1, bhi, blo); }
;         const float bg = P.b_gate_up[h * 128 + 16 * w + fr];
.LBB0_480:
	s_and_saveexec_b64 s[36:37], s[4:5]
	s_cbranch_execz .LBB0_482
	s_cmp_lg_u32 s98, 0
	s_cbranch_scc1 .Lp2_nowait0
	s_waitcnt vmcnt(0)
	s_branch .Lp2_w0done
.Lp2_nowait0:
	s_waitcnt vmcnt(2)
.Lp2_w0done:
	ds_write_b128 v88, v[0:3]
.LBB0_482:
	s_or_b64 exec, exec, s[36:37]
.Lp2_nopf:
	s_ashr_i32 s82, s80, 6
	s_lshl_b32 s36, s82, 7
	s_and_b32 s42, s36, 0x180
	v_mov_b32_e32 v24, 0
	v_mov_b32_e32 v25, 0
	v_mov_b32_e32 v26, 0
	v_mov_b32_e32 v27, 0
	v_mov_b32_e32 v20, 0
	v_mov_b32_e32 v21, 0
	v_mov_b32_e32 v22, 0
	v_mov_b32_e32 v23, 0
	s_cmp_lg_u32 s98, 0
	s_cbranch_scc1 .Lp2_hoisted
	s_and_saveexec_b64 s[36:37], s[6:7]
	s_cbranch_execz .LBB0_484
	v_or_b32_e32 v28, s42, v80
	v_or_b32_e32 v26, 0x400, v28
	v_add_u32_e32 v20, v28, v81
	v_add_u32_e32 v24, v26, v81
	v_add_u32_e32 v26, v26, v82
	v_or_b32_e32 v30, 0x600, v28
	v_ashrrev_i32_e32 v21, 31, v20
	v_add_u32_e32 v22, v28, v82
	v_ashrrev_i32_e32 v25, 31, v24
	v_ashrrev_i32_e32 v27, 31, v26
	v_add_u32_e32 v28, v30, v81
	v_add_u32_e32 v30, v30, v82
	v_lshl_add_u64 v[20:21], v[20:21], 2, s[54:55]
	v_ashrrev_i32_e32 v23, 31, v22
	v_lshl_add_u64 v[24:25], v[24:25], 2, s[54:55]
	v_lshl_add_u64 v[26:27], v[26:27], 2, s[54:55]
	v_ashrrev_i32_e32 v29, 31, v28
	v_ashrrev_i32_e32 v31, 31, v30
	v_lshl_add_u64 v[22:23], v[22:23], 2, s[54:55]
	v_lshl_add_u64 v[28:29], v[28:29], 2, s[54:55]
	v_lshl_add_u64 v[30:31], v[30:31], 2, s[54:55]
	global_load_dword v34, v[20:21], off
	global_load_dword v36, v[22:23], off
	global_load_dword v37, v[22:23], off offset:2048
	s_nop 0
	global_load_dword v24, v[24:25], off
	s_nop 0
	global_load_dword v26, v[26:27], off
	s_nop 0
	global_load_dword v25, v[28:29], off
	global_load_dword v27, v[30:31], off
	global_load_dword v35, v[20:21], off offset:2048
	s_waitcnt vmcnt(7)
	v_and_b32_sdwa v20, v34, v95 dst_sel:DWORD dst_unused:UNUSED_PAD src0_sel:WORD_1 src1_sel:DWORD
	s_waitcnt vmcnt(6)
	v_and_b32_sdwa v22, v36, v95 dst_sel:DWORD dst_unused:UNUSED_PAD src0_sel:WORD_1 src1_sel:DWORD
	s_waitcnt vmcnt(5)
	v_and_b32_sdwa v21, v37, v95 dst_sel:DWORD dst_unused:UNUSED_PAD src0_sel:WORD_1 src1_sel:DWORD
	v_add3_u32 v33, v34, v20, s86
	s_waitcnt vmcnt(4)
	v_and_b32_sdwa v29, v24, v95 dst_sel:DWORD dst_unused:UNUSED_PAD src0_sel:WORD_1 src1_sel:DWORD
	s_waitcnt vmcnt(2)
	v_and_b32_sdwa v20, v25, v95 dst_sel:DWORD dst_unused:UNUSED_PAD src0_sel:WORD_1 src1_sel:DWORD
	s_waitcnt vmcnt(1)
	v_and_b32_sdwa v31, v27, v95 dst_sel:DWORD dst_unused:UNUSED_PAD src0_sel:WORD_1 src1_sel:DWORD
	s_waitcnt vmcnt(0)
	v_and_b32_sdwa v23, v35, v95 dst_sel:DWORD dst_unused:UNUSED_PAD src0_sel:WORD_1 src1_sel:DWORD
	v_and_b32_sdwa v38, v26, v95 dst_sel:DWORD dst_unused:UNUSED_PAD src0_sel:WORD_1 src1_sel:DWORD
	v_add3_u32 v30, v37, v21, s86
	v_add3_u32 v22, v36, v22, s86
	v_add3_u32 v23, v35, v23, s86
	v_add3_u32 v40, v25, v20, s86
	v_add3_u32 v41, v24, v29, s86
	v_add3_u32 v42, v27, v31, s86
	v_add3_u32 v43, v26, v38, s86
	v_and_b32_e32 v28, 0xffff0000, v33
	v_and_b32_e32 v21, 0xffff0000, v30
	v_and_b32_e32 v20, 0xffff0000, v22
	v_cvt_pk_bf16_f32 v22, v36, v37
	v_and_b32_e32 v29, 0xffff0000, v23
	v_and_b32_e32 v31, 0xffff0000, v40
	v_and_b32_e32 v30, 0xffff0000, v41
	v_and_b32_e32 v39, 0xffff0000, v42
	v_and_b32_e32 v38, 0xffff0000, v43
	v_pk_add_f32 v[36:37], v[36:37], v[20:21] neg_lo:[0,1] neg_hi:[0,1]
	v_pk_add_f32 v[28:29], v[34:35], v[28:29] neg_lo:[0,1] neg_hi:[0,1]
	v_cvt_pk_bf16_f32 v21, v24, v25
	v_pk_add_f32 v[24:25], v[24:25], v[30:31] neg_lo:[0,1] neg_hi:[0,1]
	v_cvt_pk_bf16_f32 v23, v26, v27
	v_pk_add_f32 v[26:27], v[26:27], v[38:39] neg_lo:[0,1] neg_hi:[0,1]
	v_cvt_pk_bf16_f32 v20, v34, v35
	v_cvt_pk_bf16_f32 v138, v36, v37
	v_cvt_pk_bf16_f32 v27, v26, v27
	v_cvt_pk_bf16_f32 v25, v24, v25
	v_cvt_pk_bf16_f32 v24, v28, v29
	v_mov_b32_e32 v26, v138

; #define LAS __attribute__((address_space(3)))
; __device__ __forceinline__ void phase_gla_pre(const Params& P, LAS unsigned char* lds, bool dry) {
;     ...
;         for (int tt = 0; tt < 4; ++tt) {
;             bf16x8 ahi = (bf16x8){0, 0, 0, 0, 0, 0, 0, 0}, alo = ahi;
;             if (g < 2) { const f32x4 l0 = *(const LAS f32x4*)(Llr + (16 * tt + fr) * 16 + 8 * g), l1 = *(const LAS f32x4*)(Llr + (16 * tt + fr) * 16 + 8 * g + 4); split8(l0, l1, ahi, alo); }
;             f32x4 acc = (f32x4){bg, bg, bg, bg};
;             acc = __builtin_amdgcn_mfma_f32_16x16x32_bf16(alo, bhi, acc, 0, 0, 0); acc = __builtin_amdgcn_mfma_f32_16x16x32_bf16(ahi, blo, acc, 0, 0, 0); acc = __builtin_amdgcn_mfma_f32_16x16x32_bf16(ahi, bhi, acc, 0, 0, 0);
;             float pr[4];
; #pragma unroll
;             for (int r = 0; r < 4; ++r) { const float lg = acc[r]; const float ls = fminf(lg, 0.f) - __logf(1.0f + __expf(-fabsf(lg))); pr[r] = ls * (1.0f / 16.0f) + (r ? pr[r - 1] : 0.f); }
;             const float T = pr[3];
;             const float u1 = __shfl_up(T, 16), s1 = T + (g >= 1 ? u1 : 0.f);
;             const float u2 = __shfl_up(s1, 32), s2 = s1 + (g >= 2 ? u2 : 0.f);
;             const float base = run + (s2 - T); run += __shfl(s2, 48 + fr);
; #pragma unroll
;             for (int r = 0; r < 4; ++r) *(LAS float*)(Lb + (16 * tt + 4 * g + r) * BP + (16 * w + fr) * 4) = base + pr[r];
.Lp2_nowait1:
	s_waitcnt vmcnt(2)
	s_and_b32 s98, s38, 0xff
	s_cselect_b32 s98, 0, 1
	s_nop 1
	v_mfma_f32_16x16x32_bf16 v[32:35], v[100:103], v[140:143], v[252:255]
	v_mfma_f32_16x16x32_bf16 v[32:35], v[104:107], v[144:147], v[32:35]
	v_mfma_f32_16x16x32_bf16 v[32:35], v[104:107], v[140:143], v[32:35]
	s_nop 7
	v_min_f32_e32 v36, 0, v32
	v_mul_f32_e64 v32, |v32|, s89
	v_exp_f32_e32 v32, v32
	v_mul_f32_e64 v37, |v33|, s89
	v_exp_f32_e32 v37, v37
	v_add_f32_e32 v32, 1.0, v32
	v_add_f32_e32 v37, 1.0, v37
	v_log_f32_e32 v32, v32
	v_log_f32_e32 v37, v37
	v_mul_f32_e32 v39, 0x3d800000, v32
	v_min_f32_e32 v33, 0, v33
	v_fma_f32 v32, v36, s93, -v39
	v_mul_f32_e32 v36, 0x3d800000, v37
	v_mul_f32_e64 v37, |v34|, s89
	v_exp_f32_e32 v37, v37
	v_fma_f32 v33, v33, s93, -v36
	v_add_f32_e32 v36, 1.0, v37
	s_nop 1
	v_log_f32_e32 v36, v36
	v_add_f32_e32 v37, v33, v32
	v_min_f32_e32 v33, 0, v34
	v_mul_f32_e32 v34, 0x3d800000, v36
	s_nop 0
	v_mul_f32_e64 v36, |v35|, s89
	v_exp_f32_e32 v36, v36
	v_fma_f32 v33, v33, s93, -v34
	v_add_u32_e32 v38, 0x8800, v98
	v_add_f32_e32 v34, 1.0, v36
	s_nop 1
	v_log_f32_e32 v34, v34
	v_add_f32_e32 v36, v33, v37
	v_min_f32_e32 v33, 0, v35
	v_mul_f32_e32 v35, 0x3d800000, v34
	s_nop 1
	v_fma_f32 v33, v33, s93, -v35
	v_add_f32_e32 v34, v33, v36
	ds_bpermute_b32 v33, v83, v34
	s_waitcnt lgkmcnt(0)
	v_cndmask_b32_e64 v33, v33, 0, s[8:9]
	v_add_f32_e32 v33, v33, v34
	ds_bpermute_b32 v35, v84, v33
	s_waitcnt lgkmcnt(0)
	v_cndmask_b32_e64 v35, 0, v35, s[10:11]
	v_add_f32_e32 v33, v35, v33
	v_sub_f32_e32 v35, v33, v34
	ds_bpermute_b32 v33, v85, v33
	v_add_f32_e32 v35, 0, v35
	v_add_f32_e32 v32, v32, v35
	v_add_f32_e32 v37, v37, v35
	ds_write2_b32 v38, v32, v37 offset1:132
	v_add_f32_e32 v32, v36, v35
	v_add_f32_e32 v34, v34, v35
	v_add_u32_e32 v35, 0x8c00, v98
	ds_write2_b32 v35, v32, v34 offset0:8 offset1:140
	v_mov_b32_e32 v108, 0
	v_mov_b32_e32 v109, 0
	v_mov_b32_e32 v110, 0
	v_mov_b32_e32 v111, 0
	v_mov_b32_e32 v112, 0
	v_mov_b32_e32 v113, 0
	v_mov_b32_e32 v114, 0
	v_mov_b32_e32 v115, 0
	s_and_saveexec_b64 s[36:37], s[6:7]
	s_cbranch_execz .LBB0_488
	ds_read_b128 v[34:37], v96 offset:1024
	ds_read_b128 v[38:41], v96 offset:1040
	s_waitcnt lgkmcnt(1)
	v_cvt_pk_bf16_f32 v112, v34, v35
	v_lshlrev_b32_e32 v132, 16, v112
	v_and_b32_e32 v133, 0xffff0000, v112
	v_pk_add_f32 v[34:35], v[34:35], v[132:133] neg_lo:[0,1] neg_hi:[0,1]
	v_cvt_pk_bf16_f32 v113, v36, v37
	v_lshlrev_b32_e32 v134, 16, v113
	v_and_b32_e32 v135, 0xffff0000, v113
	v_pk_add_f32 v[36:37], v[36:37], v[134:135] neg_lo:[0,1] neg_hi:[0,1]
	s_waitcnt lgkmcnt(0)
	v_cvt_pk_bf16_f32 v114, v38, v39
	v_lshlrev_b32_e32 v136, 16, v114
	v_and_b32_e32 v137, 0xffff0000, v114
	v_pk_add_f32 v[38:39], v[38:39], v[136:137] neg_lo:[0,1] neg_hi:[0,1]
	v_cvt_pk_bf16_f32 v115, v40, v41
	v_lshlrev_b32_e32 v138, 16, v115
	v_and_b32_e32 v139, 0xffff0000, v115
	v_pk_add_f32 v[40:41], v[40:41], v[138:139] neg_lo:[0,1] neg_hi:[0,1]
	s_nop 0
	v_cvt_pk_bf16_f32 v111, v40, v41
	v_cvt_pk_bf16_f32 v110, v38, v39
	v_cvt_pk_bf16_f32 v109, v36, v37
	v_cvt_pk_bf16_f32 v108, v34, v35
